# v65 re-partitioned: P4 idle tail converts segment 12 + segment 11 blocks 0-63; P5's remaining 1792 items run only on workgroups 192-255 (which have no q-up unit)
# speedup vs baseline: 1.0062x; 1.0017x over previous
.Lp4c_done:
	s_waitcnt vmcnt(0) lgkmcnt(0)
	s_barrier
	s_lshl_b32 s12, s82, 3
	s_add_i32 s12, s12, s83
	s_movk_i32 s14, 0x200
	s_mov_b64 s[0:1], s[70:71]
	s_load_dwordx2 s[4:5], s[0:1], 0xb8
	s_lshl_b32 s0, s83, 14
	s_mov_b64 s[6:7], s[70:71]
	s_add_i32 s2, s0, 0
	s_waitcnt lgkmcnt(0)
	v_mbcnt_hi_u32_b32 v168, -1, v187
	s_add_u32 s8, s6, 0x98
	s_addc_u32 s9, s7, 0
	v_lshlrev_b32_e32 v3, 3, v168
	s_add_u32 s16, s6, 0xa8
	v_lshrrev_b32_e32 v42, 3, v168
	v_and_b32_e32 v3, 56, v3
	s_addc_u32 s17, s7, 0
	v_and_b32_e32 v144, 64, v168
	v_mul_u32_u24_e32 v4, 0x84, v3
	v_lshlrev_b32_e32 v32, 2, v42
	s_abs_i32 s15, s14
	v_add_u32_e32 v44, 8, v42
	v_or_b32_e32 v1, v42, v144
	v_add3_u32 v47, s2, v4, v32
	v_cvt_f32_u32_e32 v4, s15
	v_or_b32_e32 v45, 16, v42
	v_lshlrev_b32_e32 v48, 2, v1
	v_or_b32_e32 v1, v44, v144
	v_add_u32_e32 v46, 24, v42
	v_lshlrev_b32_e32 v49, 2, v1
	v_or_b32_e32 v1, v45, v144
	v_lshlrev_b32_e32 v50, 2, v1
	v_or_b32_e32 v1, v46, v144
	v_lshlrev_b32_e32 v51, 2, v1
	v_rcp_iflag_f32_e32 v1, v4
	s_load_dwordx2 s[0:1], s[6:7], 0xb8
	v_mov_b32_e32 v35, 0
	v_lshlrev_b32_e32 v34, 1, v3
	v_mul_f32_e32 v1, 0x4f7ffffe, v1
	v_cvt_u32_f32_e32 v1, v1
	s_waitcnt lgkmcnt(0)
	v_lshl_add_u64 v[36:37], s[0:1], 0, v[34:35]
	s_sub_i32 s0, 0, s15
	v_lshlrev_b32_e32 v0, 2, v168
	v_readfirstlane_b32 s1, v1
	v_add_u32_e32 v2, 56, v42
	s_mul_i32 s0, s0, s1
	v_and_b32_e32 v0, 28, v0
	v_and_or_b32 v2, v2, 63, v144
	s_mul_hi_u32 s0, s1, s0
	s_mov_b32 s13, 0
	v_lshl_add_u32 v33, v0, 2, s2
	v_mul_u32_u24_e32 v43, 0x84, v42
	v_or_b32_e32 v52, 0x80, v48
	v_add_u32_e32 v53, 0xa0, v48
	v_or_b32_e32 v54, 0xc0, v48
	v_lshlrev_b32_e32 v55, 2, v2
	s_add_i32 s33, s1, s0
	s_mov_b32 s34, 0x8000
	s_mov_b64 s[0:1], -1
	s_mov_b64 s[18:19], -1
	v_lshlrev_b32_e32 v34, 2, v0
	s_branch .Lp4d_662

.Lp4d_662:
	s_xor_b64 s[20:21], s[0:1], -1
	s_and_b64 vcc, exec, s[20:21]
	s_cbranch_vccnz .Lp4d_664
	s_waitcnt lgkmcnt(0)
	s_load_dwordx2 s[24:25], s[6:7], 0x90
	s_load_dwordx2 s[22:23], s[6:7], 0xa0
	s_movk_i32 s28, 0x40
	s_movk_i32 s35, 0x400
	s_mov_b64 s[26:27], 0xb00
	s_mov_b64 s[2:3], 0xa00000
	s_mov_b64 s[0:1], s[8:9]
	s_branch .Lp4d_665

.LBB0_659:
	s_cmp_lt_i32 s81, 6
	s_cselect_b64 s[2:3], -1, 0
	s_and_b64 s[10:11], s[2:3], s[0:1]
	s_andn2_b64 vcc, exec, s[10:11]
	s_cbranch_vccnz .LBB0_831
	s_mov_b32 s100, s12
	s_mov_b32 s101, s14
	s_cmpk_lg_i32 s79, 0x100
	s_cbranch_scc1 .Lp5c_std
	s_movk_i32 s14, 0x200
	s_sub_i32 s0, s82, 0xc0
	s_lshl_b32 s0, s0, 3
	s_add_i32 s0, s0, s83
	s_addk_i32 s0, 0x400
	s_cmpk_ge_i32 s82, 0xc0
	s_cselect_b32 s12, s0, 0x3fffffff
.Lp5c_std:
	s_mov_b64 s[0:1], s[70:71]
	s_load_dwordx2 s[4:5], s[0:1], 0xb8
	s_lshl_b32 s0, s83, 14
	s_mov_b64 s[6:7], s[70:71]
	s_add_i32 s2, s0, 0
	s_waitcnt lgkmcnt(0)
	v_mbcnt_hi_u32_b32 v168, -1, v187
	s_add_u32 s8, s6, 0x98
	s_addc_u32 s9, s7, 0
	v_lshlrev_b32_e32 v3, 3, v168
	s_add_u32 s16, s6, 0xa8
	v_lshrrev_b32_e32 v42, 3, v168
	v_and_b32_e32 v3, 56, v3
	s_addc_u32 s17, s7, 0
	v_and_b32_e32 v144, 64, v168
	v_mul_u32_u24_e32 v4, 0x84, v3
	v_lshlrev_b32_e32 v32, 2, v42
	s_abs_i32 s15, s14
	v_add_u32_e32 v44, 8, v42
	v_or_b32_e32 v1, v42, v144
	v_add3_u32 v47, s2, v4, v32
	v_cvt_f32_u32_e32 v4, s15
	v_or_b32_e32 v45, 16, v42
	v_lshlrev_b32_e32 v48, 2, v1
	v_or_b32_e32 v1, v44, v144
	v_add_u32_e32 v46, 24, v42
	v_lshlrev_b32_e32 v49, 2, v1
	v_or_b32_e32 v1, v45, v144
	v_lshlrev_b32_e32 v50, 2, v1
	v_or_b32_e32 v1, v46, v144
	v_lshlrev_b32_e32 v51, 2, v1
	v_rcp_iflag_f32_e32 v1, v4
	s_load_dwordx2 s[0:1], s[6:7], 0xb8
	v_mov_b32_e32 v35, 0
	v_lshlrev_b32_e32 v34, 1, v3
	v_mul_f32_e32 v1, 0x4f7ffffe, v1
	v_cvt_u32_f32_e32 v1, v1
	s_waitcnt lgkmcnt(0)
	v_lshl_add_u64 v[36:37], s[0:1], 0, v[34:35]
	s_sub_i32 s0, 0, s15
	v_lshlrev_b32_e32 v0, 2, v168
	v_readfirstlane_b32 s1, v1
	v_add_u32_e32 v2, 56, v42
	s_mul_i32 s0, s0, s1
	v_and_b32_e32 v0, 28, v0
	v_and_or_b32 v2, v2, 63, v144
	s_mul_hi_u32 s0, s1, s0
	s_mov_b32 s13, 0
	v_lshl_add_u32 v33, v0, 2, s2
	v_mul_u32_u24_e32 v43, 0x84, v42
	v_or_b32_e32 v52, 0x80, v48
	v_add_u32_e32 v53, 0xa0, v48
	v_or_b32_e32 v54, 0xc0, v48
	v_lshlrev_b32_e32 v55, 2, v2
	s_add_i32 s33, s1, s0
	s_lshl_b32 s34, s79, 9
	s_cmpk_eq_i32 s79, 0x100
	s_cselect_b32 s34, 0x8000, s34
	s_mov_b64 s[0:1], -1
	s_mov_b64 s[18:19], 0
	s_cmpk_eq_i32 s79, 0x100
	s_cselect_b64 s[18:19], -1, 0
	v_lshlrev_b32_e32 v34, 2, v0
	s_branch .LBB0_662
